# hoist loop-invariant norm-weight loads out of the x->bf16 prologue row loop and the final RMSNorm row loop (removes 8 serialized vmcnt(0) round trips per row)
# speedup vs baseline: 1.0027x; 1.0027x over previous
.LBB0_50:
	s_or_b64 exec, exec, s[8:9]
	s_cmpk_gt_i32 s6, 0x1fff
	v_mbcnt_lo_u32_b32 v50, -1, 0
	s_cbranch_scc1 .LBB0_55
	v_mbcnt_hi_u32_b32 v2, -1, v50
	v_and_b32_e32 v1, 64, v2
	v_add_u32_e32 v3, 64, v1
	v_xor_b32_e32 v1, 1, v2
	v_cmp_lt_i32_e32 vcc, v1, v3
	v_xor_b32_e32 v4, 2, v2
	s_load_dwordx4 s[12:15], s[0:1], 0x0
	v_cndmask_b32_e32 v1, v2, v1, vcc
	v_cmp_lt_i32_e32 vcc, v4, v3
	v_lshlrev_b32_e32 v34, 4, v8
	v_mov_b32_e32 v35, 0
	v_cndmask_b32_e32 v4, v2, v4, vcc
	v_lshlrev_b32_e32 v51, 2, v4
	v_xor_b32_e32 v4, 4, v2
	v_cmp_lt_i32_e32 vcc, v4, v3
	s_waitcnt lgkmcnt(0)
	v_lshl_add_u64 v[36:37], s[14:15], 0, v[34:35]
	s_mov_b64 s[8:9], 0x1400
	v_cndmask_b32_e32 v4, v2, v4, vcc
	v_lshlrev_b32_e32 v52, 2, v4
	v_xor_b32_e32 v4, 8, v2
	v_cmp_lt_i32_e32 vcc, v4, v3
	v_lshl_add_u64 v[40:41], v[36:37], 0, s[8:9]
	s_mov_b64 s[8:9], 0x1800
	v_cndmask_b32_e32 v4, v2, v4, vcc
	v_lshl_add_u64 v[42:43], v[36:37], 0, s[8:9]
	s_mov_b64 s[8:9], 0x1c00
	s_ashr_i32 s7, s6, 31
	v_lshlrev_b32_e32 v53, 2, v4
	v_xor_b32_e32 v4, 16, v2
	v_lshl_add_u64 v[44:45], v[36:37], 0, s[8:9]
	s_lshl_b64 s[8:9], s[6:7], 2
	v_cmp_lt_i32_e32 vcc, v4, v3
	s_add_u32 s14, s8, 0x28064000
	v_readlane_b32 s2, v251, 6
	v_cndmask_b32_e32 v4, v2, v4, vcc
	s_addc_u32 s15, s9, 0
	s_mov_b32 s16, s2
	s_ashr_i32 s17, s2, 31
	v_lshlrev_b32_e32 v54, 2, v4
	v_xor_b32_e32 v4, 32, v2
	s_lshl_b64 s[8:9], s[16:17], 2
	s_lshl_b64 s[10:11], s[6:7], 13
	v_cmp_lt_i32_e32 vcc, v4, v3
	s_add_u32 s10, s12, s10
	s_addc_u32 s11, s13, s11
	v_cndmask_b32_e32 v2, v2, v4, vcc
	v_lshlrev_b32_e32 v55, 2, v2
	s_mov_b64 s[4:5], 0x1000
	v_readlane_b32 s3, v251, 7
	v_lshl_add_u64 v[2:3], s[10:11], 0, v[34:35]
	v_lshl_add_u64 v[38:39], v[36:37], 0, s[4:5]
	v_lshl_add_u64 v[46:47], v[2:3], 0, s[4:5]
	s_lshl_b64 s[4:5], s[6:7], 12
	v_writelane_b32 v251, s2, 6
	v_lshlrev_b32_e32 v1, 2, v1
	v_cmp_eq_u32_e32 vcc, 0, v8
	s_lshl_b64 s[10:11], s[16:17], 13
	v_lshl_or_b32 v48, v8, 3, s4
	v_mov_b32_e32 v49, s5
	v_writelane_b32 v251, s3, 7
	s_lshl_b64 s[12:13], s[16:17], 12
	s_movk_i32 s7, 0x7fff
	s_mov_b32 s16, 0xda40000
	v_mov_b32_e32 v34, 1
	global_load_dwordx4 v[72:75], v[36:37], off
	global_load_dwordx4 v[76:79], v[36:37], off offset:1024
	global_load_dwordx4 v[80:83], v[36:37], off offset:2048
	global_load_dwordx4 v[84:87], v[36:37], off offset:3072
	global_load_dwordx4 v[88:91], v[38:39], off
	global_load_dwordx4 v[92:95], v[40:41], off
	global_load_dwordx4 v[96:99], v[42:43], off
	global_load_dwordx4 v[100:103], v[44:45], off
	s_branch .LBB0_53
.LBB0_52:
	s_or_b64 exec, exec, s[4:5]
	s_waitcnt lgkmcnt(0)
	v_lshl_add_u64 v[60:61], s[24:25], 0, v[48:49]
	v_add_co_u32_e64 v60, s[4:5], s16, v60
	v_readlane_b32 s2, v251, 6
	s_nop 0
	v_addc_co_u32_e64 v61, s[4:5], 0, v61, s[4:5]
	s_add_i32 s6, s6, s2
	s_add_u32 s14, s14, s8
	s_addc_u32 s15, s15, s9
	v_lshl_add_u64 v[46:47], v[46:47], 0, s[10:11]
	s_cmpk_lt_i32 s6, 0x2000
	v_lshl_add_u64 v[48:49], v[48:49], 0, s[12:13]
	v_readlane_b32 s3, v251, 7
	v_pk_mul_f32 v[32:33], v[32:33], v[74:75]
	v_pk_mul_f32 v[30:31], v[30:31], v[72:73]
	v_and_b32_sdwa v58, v33, v34 dst_sel:DWORD dst_unused:UNUSED_PAD src0_sel:WORD_1 src1_sel:DWORD
	v_and_b32_sdwa v59, v31, v34 dst_sel:DWORD dst_unused:UNUSED_PAD src0_sel:WORD_1 src1_sel:DWORD
	v_and_b32_sdwa v56, v32, v34 dst_sel:DWORD dst_unused:UNUSED_PAD src0_sel:WORD_1 src1_sel:DWORD
	v_and_b32_sdwa v57, v30, v34 dst_sel:DWORD dst_unused:UNUSED_PAD src0_sel:WORD_1 src1_sel:DWORD
	v_add3_u32 v33, v33, v58, s7
	v_add3_u32 v31, v31, v59, s7
	v_add3_u32 v30, v30, v57, s7
	v_add3_u32 v32, v32, v56, s7
	v_and_b32_e32 v33, 0xffff0000, v33
	v_and_b32_e32 v56, 0xffff0000, v31
	v_or_b32_sdwa v31, v33, v32 dst_sel:DWORD dst_unused:UNUSED_PAD src0_sel:DWORD src1_sel:WORD_1
	v_or_b32_sdwa v30, v56, v30 dst_sel:DWORD dst_unused:UNUSED_PAD src0_sel:DWORD src1_sel:WORD_1
	global_store_dwordx2 v[60:61], v[30:31], off
	v_pk_mul_f32 v[28:29], v[28:29], v[78:79]
	v_pk_mul_f32 v[26:27], v[26:27], v[76:77]
	v_and_b32_sdwa v32, v29, v34 dst_sel:DWORD dst_unused:UNUSED_PAD src0_sel:WORD_1 src1_sel:DWORD
	v_and_b32_sdwa v33, v27, v34 dst_sel:DWORD dst_unused:UNUSED_PAD src0_sel:WORD_1 src1_sel:DWORD
	v_and_b32_sdwa v30, v28, v34 dst_sel:DWORD dst_unused:UNUSED_PAD src0_sel:WORD_1 src1_sel:DWORD
	v_and_b32_sdwa v31, v26, v34 dst_sel:DWORD dst_unused:UNUSED_PAD src0_sel:WORD_1 src1_sel:DWORD
	v_add3_u32 v29, v29, v32, s7
	v_add3_u32 v27, v27, v33, s7
	v_add3_u32 v26, v26, v31, s7
	v_add3_u32 v28, v28, v30, s7
	v_and_b32_e32 v29, 0xffff0000, v29
	v_and_b32_e32 v30, 0xffff0000, v27
	v_or_b32_sdwa v27, v29, v28 dst_sel:DWORD dst_unused:UNUSED_PAD src0_sel:DWORD src1_sel:WORD_1
	v_or_b32_sdwa v26, v30, v26 dst_sel:DWORD dst_unused:UNUSED_PAD src0_sel:DWORD src1_sel:WORD_1
	global_store_dwordx2 v[60:61], v[26:27], off offset:512
	v_pk_mul_f32 v[24:25], v[24:25], v[82:83]
	v_pk_mul_f32 v[22:23], v[22:23], v[80:81]
	v_and_b32_sdwa v28, v25, v34 dst_sel:DWORD dst_unused:UNUSED_PAD src0_sel:WORD_1 src1_sel:DWORD
	v_and_b32_sdwa v29, v23, v34 dst_sel:DWORD dst_unused:UNUSED_PAD src0_sel:WORD_1 src1_sel:DWORD
	v_and_b32_sdwa v26, v24, v34 dst_sel:DWORD dst_unused:UNUSED_PAD src0_sel:WORD_1 src1_sel:DWORD
	v_and_b32_sdwa v27, v22, v34 dst_sel:DWORD dst_unused:UNUSED_PAD src0_sel:WORD_1 src1_sel:DWORD
	v_add3_u32 v25, v25, v28, s7
	v_add3_u32 v23, v23, v29, s7
	v_add3_u32 v22, v22, v27, s7
	v_add3_u32 v24, v24, v26, s7
	v_and_b32_e32 v25, 0xffff0000, v25
	v_and_b32_e32 v26, 0xffff0000, v23
	v_or_b32_sdwa v23, v25, v24 dst_sel:DWORD dst_unused:UNUSED_PAD src0_sel:DWORD src1_sel:WORD_1
	v_or_b32_sdwa v22, v26, v22 dst_sel:DWORD dst_unused:UNUSED_PAD src0_sel:DWORD src1_sel:WORD_1
	global_store_dwordx2 v[60:61], v[22:23], off offset:1024
	v_pk_mul_f32 v[20:21], v[20:21], v[86:87]
	v_pk_mul_f32 v[18:19], v[18:19], v[84:85]
	v_and_b32_sdwa v24, v21, v34 dst_sel:DWORD dst_unused:UNUSED_PAD src0_sel:WORD_1 src1_sel:DWORD
	v_and_b32_sdwa v25, v19, v34 dst_sel:DWORD dst_unused:UNUSED_PAD src0_sel:WORD_1 src1_sel:DWORD
	v_and_b32_sdwa v22, v20, v34 dst_sel:DWORD dst_unused:UNUSED_PAD src0_sel:WORD_1 src1_sel:DWORD
	v_and_b32_sdwa v23, v18, v34 dst_sel:DWORD dst_unused:UNUSED_PAD src0_sel:WORD_1 src1_sel:DWORD
	v_add3_u32 v21, v21, v24, s7
	v_add3_u32 v19, v19, v25, s7
	v_add3_u32 v18, v18, v23, s7
	v_add3_u32 v20, v20, v22, s7
	v_and_b32_e32 v21, 0xffff0000, v21
	v_and_b32_e32 v22, 0xffff0000, v19
	v_or_b32_sdwa v19, v21, v20 dst_sel:DWORD dst_unused:UNUSED_PAD src0_sel:DWORD src1_sel:WORD_1
	v_or_b32_sdwa v18, v22, v18 dst_sel:DWORD dst_unused:UNUSED_PAD src0_sel:DWORD src1_sel:WORD_1
	global_store_dwordx2 v[60:61], v[18:19], off offset:1536
	v_pk_mul_f32 v[16:17], v[16:17], v[90:91]
	v_pk_mul_f32 v[14:15], v[14:15], v[88:89]
	v_and_b32_sdwa v20, v17, v34 dst_sel:DWORD dst_unused:UNUSED_PAD src0_sel:WORD_1 src1_sel:DWORD
	v_and_b32_sdwa v21, v15, v34 dst_sel:DWORD dst_unused:UNUSED_PAD src0_sel:WORD_1 src1_sel:DWORD
	v_and_b32_sdwa v18, v16, v34 dst_sel:DWORD dst_unused:UNUSED_PAD src0_sel:WORD_1 src1_sel:DWORD
	v_and_b32_sdwa v19, v14, v34 dst_sel:DWORD dst_unused:UNUSED_PAD src0_sel:WORD_1 src1_sel:DWORD
	v_add3_u32 v17, v17, v20, s7
	v_add3_u32 v15, v15, v21, s7
	v_add3_u32 v14, v14, v19, s7
	v_add3_u32 v16, v16, v18, s7
	v_and_b32_e32 v17, 0xffff0000, v17
	v_and_b32_e32 v18, 0xffff0000, v15
	v_or_b32_sdwa v15, v17, v16 dst_sel:DWORD dst_unused:UNUSED_PAD src0_sel:DWORD src1_sel:WORD_1
	v_or_b32_sdwa v14, v18, v14 dst_sel:DWORD dst_unused:UNUSED_PAD src0_sel:DWORD src1_sel:WORD_1
	global_store_dwordx2 v[60:61], v[14:15], off offset:2048
	v_pk_mul_f32 v[12:13], v[12:13], v[94:95]
	v_pk_mul_f32 v[10:11], v[10:11], v[92:93]
	v_and_b32_sdwa v16, v13, v34 dst_sel:DWORD dst_unused:UNUSED_PAD src0_sel:WORD_1 src1_sel:DWORD
	v_and_b32_sdwa v17, v11, v34 dst_sel:DWORD dst_unused:UNUSED_PAD src0_sel:WORD_1 src1_sel:DWORD
	v_and_b32_sdwa v14, v12, v34 dst_sel:DWORD dst_unused:UNUSED_PAD src0_sel:WORD_1 src1_sel:DWORD
	v_and_b32_sdwa v15, v10, v34 dst_sel:DWORD dst_unused:UNUSED_PAD src0_sel:WORD_1 src1_sel:DWORD
	v_add3_u32 v13, v13, v16, s7
	v_add3_u32 v11, v11, v17, s7
	v_add3_u32 v10, v10, v15, s7
	v_add3_u32 v12, v12, v14, s7
	v_and_b32_e32 v13, 0xffff0000, v13
	v_and_b32_e32 v14, 0xffff0000, v11
	v_or_b32_sdwa v11, v13, v12 dst_sel:DWORD dst_unused:UNUSED_PAD src0_sel:DWORD src1_sel:WORD_1
	v_or_b32_sdwa v10, v14, v10 dst_sel:DWORD dst_unused:UNUSED_PAD src0_sel:DWORD src1_sel:WORD_1
	global_store_dwordx2 v[60:61], v[10:11], off offset:2560
	v_pk_mul_f32 v[8:9], v[8:9], v[98:99]
	v_pk_mul_f32 v[6:7], v[6:7], v[96:97]
	v_and_b32_sdwa v12, v9, v34 dst_sel:DWORD dst_unused:UNUSED_PAD src0_sel:WORD_1 src1_sel:DWORD
	v_and_b32_sdwa v13, v7, v34 dst_sel:DWORD dst_unused:UNUSED_PAD src0_sel:WORD_1 src1_sel:DWORD
	v_and_b32_sdwa v10, v8, v34 dst_sel:DWORD dst_unused:UNUSED_PAD src0_sel:WORD_1 src1_sel:DWORD
	v_and_b32_sdwa v11, v6, v34 dst_sel:DWORD dst_unused:UNUSED_PAD src0_sel:WORD_1 src1_sel:DWORD
	v_add3_u32 v9, v9, v12, s7
	v_add3_u32 v7, v7, v13, s7
	v_add3_u32 v6, v6, v11, s7
	v_add3_u32 v8, v8, v10, s7
	v_and_b32_e32 v9, 0xffff0000, v9
	v_and_b32_e32 v10, 0xffff0000, v7
	v_or_b32_sdwa v7, v9, v8 dst_sel:DWORD dst_unused:UNUSED_PAD src0_sel:DWORD src1_sel:WORD_1
	v_or_b32_sdwa v6, v10, v6 dst_sel:DWORD dst_unused:UNUSED_PAD src0_sel:DWORD src1_sel:WORD_1
	global_store_dwordx2 v[60:61], v[6:7], off offset:3072
	v_pk_mul_f32 v[4:5], v[4:5], v[102:103]
	v_pk_mul_f32 v[2:3], v[2:3], v[100:101]
	v_and_b32_sdwa v8, v5, v34 dst_sel:DWORD dst_unused:UNUSED_PAD src0_sel:WORD_1 src1_sel:DWORD
	v_and_b32_sdwa v9, v3, v34 dst_sel:DWORD dst_unused:UNUSED_PAD src0_sel:WORD_1 src1_sel:DWORD
	v_and_b32_sdwa v6, v4, v34 dst_sel:DWORD dst_unused:UNUSED_PAD src0_sel:WORD_1 src1_sel:DWORD
	v_and_b32_sdwa v7, v2, v34 dst_sel:DWORD dst_unused:UNUSED_PAD src0_sel:WORD_1 src1_sel:DWORD
	v_add3_u32 v5, v5, v8, s7
	v_add3_u32 v3, v3, v9, s7
	v_add3_u32 v2, v2, v7, s7
	v_add3_u32 v4, v4, v6, s7
	v_and_b32_e32 v5, 0xffff0000, v5
	v_and_b32_e32 v6, 0xffff0000, v3
	v_or_b32_sdwa v3, v5, v4 dst_sel:DWORD dst_unused:UNUSED_PAD src0_sel:DWORD src1_sel:WORD_1
	v_or_b32_sdwa v2, v6, v2 dst_sel:DWORD dst_unused:UNUSED_PAD src0_sel:DWORD src1_sel:WORD_1
	global_store_dwordx2 v[60:61], v[2:3], off offset:3584
	s_cbranch_scc0 .LBB0_55

.LBB0_1166:
	s_ashr_i32 s0, s0, 6
	v_readlane_b32 s1, v251, 5
	s_add_i32 s2, s0, s1
	s_cmpk_gt_i32 s2, 0x1fff
	s_cbranch_scc1 .LBB0_1169
	v_and_b32_e32 v0, 63, v0
	v_lshlrev_b32_e32 v16, 4, v0
	v_and_b32_e32 v0, 64, v217
	v_add_u32_e32 v0, 64, v0
	v_xor_b32_e32 v1, 1, v217
	v_cmp_lt_i32_e32 vcc, v1, v0
	v_readlane_b32 s8, v250, 2
	v_mov_b32_e32 v17, 0
	v_cndmask_b32_e32 v1, v217, v1, vcc
	v_lshlrev_b32_e32 v28, 2, v1
	v_xor_b32_e32 v1, 2, v217
	v_cmp_lt_i32_e32 vcc, v1, v0
	v_readlane_b32 s9, v250, 3
	s_mov_b64 s[0:1], 0x1000
	v_cndmask_b32_e32 v1, v217, v1, vcc
	v_lshlrev_b32_e32 v29, 2, v1
	v_xor_b32_e32 v1, 4, v217
	v_cmp_lt_i32_e32 vcc, v1, v0
	v_lshl_add_u64 v[18:19], s[8:9], 0, v[16:17]
	v_lshl_add_u64 v[20:21], v[18:19], 0, s[0:1]
	v_cndmask_b32_e32 v1, v217, v1, vcc
	v_lshlrev_b32_e32 v30, 2, v1
	v_xor_b32_e32 v1, 8, v217
	v_cmp_lt_i32_e32 vcc, v1, v0
	s_mov_b64 s[0:1], 0x1400
	v_lshl_add_u64 v[22:23], v[18:19], 0, s[0:1]
	v_cndmask_b32_e32 v1, v217, v1, vcc
	s_mov_b64 s[0:1], 0x1800
	v_lshlrev_b32_e32 v31, 2, v1
	v_xor_b32_e32 v1, 16, v217
	v_lshl_add_u64 v[24:25], v[18:19], 0, s[0:1]
	s_mov_b64 s[0:1], 0x1c00
	s_ashr_i32 s3, s2, 31
	v_cmp_lt_i32_e32 vcc, v1, v0
	v_lshl_add_u64 v[26:27], v[18:19], 0, s[0:1]
	s_lshl_b64 s[0:1], s[2:3], 13
	v_readlane_b32 s12, v251, 6
	v_cndmask_b32_e32 v1, v217, v1, vcc
	s_add_u32 s4, s24, s0
	v_readlane_b32 s13, v251, 7
	v_lshlrev_b32_e32 v32, 2, v1
	v_xor_b32_e32 v1, 32, v217
	s_addc_u32 s5, s25, s1
	s_ashr_i32 s13, s12, 31
	v_readlane_b32 s10, v250, 4
	v_cmp_lt_i32_e32 vcc, v1, v0
	s_lshl_b64 s[6:7], s[12:13], 13
	v_readlane_b32 s11, v250, 5
	v_cndmask_b32_e32 v0, v217, v1, vcc
	s_add_u32 s8, s10, s0
	v_lshlrev_b32_e32 v33, 2, v0
	s_addc_u32 s9, s11, s1
	s_mov_b32 s3, 0xfa41000
	v_mov_b32_e32 v34, 0x358637bd
	s_mov_b32 s10, 0xf800000
	v_mov_b32_e32 v35, 0x260
	s_movk_i32 s11, 0x1000
	global_load_dwordx4 v[100:103], v[18:19], off
	global_load_dwordx4 v[104:107], v[18:19], off offset:1024
	global_load_dwordx4 v[108:111], v[18:19], off offset:2048
	global_load_dwordx4 v[112:115], v[18:19], off offset:3072
	global_load_dwordx4 v[116:119], v[20:21], off
	global_load_dwordx4 v[120:123], v[22:23], off
	global_load_dwordx4 v[124:127], v[24:25], off
	global_load_dwordx4 v[128:131], v[26:27], off
.LBB0_1168:
	s_nop 0
	v_lshl_add_u64 v[0:1], s[4:5], 0, v[16:17]
	v_add_co_u32_e64 v54, s[0:1], s3, v0
	v_add_co_u32_e32 v52, vcc, 0xfa40000, v0
	s_nop 0
	v_addc_co_u32_e64 v55, s[0:1], 0, v1, s[0:1]
	v_addc_co_u32_e32 v53, vcc, 0, v1, vcc
	global_load_dwordx4 v[4:7], v[54:55], off
	global_load_dwordx4 v[12:15], v[54:55], off offset:1024
	global_load_dwordx4 v[8:11], v[54:55], off offset:2048
	global_load_dwordx4 v[36:39], v[52:53], off
	global_load_dwordx4 v[40:43], v[52:53], off offset:1024
	global_load_dwordx4 v[44:47], v[52:53], off offset:2048
	global_load_dwordx4 v[48:51], v[52:53], off offset:3072
	global_load_dwordx4 v[0:3], v[54:55], off offset:3072
	v_lshl_add_u64 v[56:57], s[8:9], 0, v[16:17]
	s_add_i32 s2, s2, s12
	s_add_u32 s4, s4, s6
	s_addc_u32 s5, s5, s7
	s_add_u32 s8, s8, s6
	s_addc_u32 s9, s9, s7
	s_cmpk_lt_i32 s2, 0x2000
	s_waitcnt vmcnt(7)
	v_mul_f32_e32 v81, v4, v4
	s_waitcnt vmcnt(6)
	v_pk_mul_f32 v[58:59], v[14:15], v[14:15]
	v_pk_mul_f32 v[60:61], v[12:13], v[12:13]
	s_waitcnt vmcnt(5)
	v_mul_f32_e32 v62, v9, v9
	v_mul_f32_e32 v64, v11, v11
	s_waitcnt vmcnt(4)
	v_mov_b32_e32 v68, v37
	s_waitcnt vmcnt(3)
	v_mov_b32_e32 v69, v41
	v_mov_b32_e32 v72, v39
	v_mov_b32_e32 v73, v43
	s_waitcnt vmcnt(0)
	v_mul_f32_e32 v89, v2, v2
	v_mul_f32_e32 v90, v3, v3
	v_mov_b32_e32 v66, v36
	v_mov_b32_e32 v67, v40
	v_mov_b32_e32 v70, v38
	v_mov_b32_e32 v71, v42
	v_pk_mul_f32 v[74:75], v[46:47], v[46:47]
	v_pk_mul_f32 v[76:77], v[44:45], v[44:45]
	v_pk_mov_b32 v[82:83], v[60:61], v[58:59] op_sel:[1,0]
	v_mov_b32_e32 v61, v59
	v_pk_fma_f32 v[58:59], v[8:9], v[8:9], v[62:63] op_sel_hi:[1,1,0]
	v_pk_fma_f32 v[62:63], v[10:11], v[10:11], v[64:65] op_sel_hi:[1,1,0]
	v_pk_mul_f32 v[64:65], v[68:69], v[68:69]
	v_pk_mul_f32 v[68:69], v[72:73], v[72:73]
	v_pk_mov_b32 v[72:73], v[76:77], v[74:75] op_sel:[1,0]
	v_mov_b32_e32 v77, v75
	v_mov_b32_e32 v59, v89
	v_mov_b32_e32 v63, v90
	v_pk_fma_f32 v[64:65], v[66:67], v[66:67], v[64:65]
	v_pk_fma_f32 v[66:67], v[70:71], v[70:71], v[68:69]
	v_mul_f32_e32 v78, v49, v49
	v_mul_f32_e32 v80, v51, v51
	v_pk_add_f32 v[68:69], v[72:73], v[76:77]
	v_pk_add_f32 v[58:59], v[58:59], v[62:63]
	v_pk_add_f32 v[62:63], v[64:65], v[66:67]
	v_mul_f32_e32 v84, v5, v5
	v_mul_f32_e32 v85, v6, v6
	v_mul_f32_e32 v86, v7, v7
	v_pk_fma_f32 v[74:75], v[48:49], v[48:49], v[78:79] op_sel_hi:[1,1,0]
	v_pk_fma_f32 v[78:79], v[50:51], v[50:51], v[80:81] op_sel_hi:[1,1,0]
	v_pk_add_f32 v[64:65], v[68:69], v[68:69] op_sel:[0,1] op_sel_hi:[1,0]
	v_pk_add_f32 v[62:63], v[62:63], v[62:63] op_sel:[0,1] op_sel_hi:[1,0]
	v_mov_b32_e32 v75, v85
	v_mov_b32_e32 v79, v86
	v_mov_b32_e32 v65, v84
	v_mov_b32_e32 v63, v81
	v_pk_add_f32 v[66:67], v[74:75], v[78:79]
	v_pk_add_f32 v[62:63], v[62:63], v[64:65]
	v_pk_add_f32 v[60:61], v[82:83], v[60:61]
	v_pk_add_f32 v[62:63], v[62:63], v[66:67]
	v_mul_f32_e32 v87, v0, v0
	v_mul_f32_e32 v88, v1, v1
	v_pk_add_f32 v[60:61], v[60:61], v[60:61] op_sel:[0,1] op_sel_hi:[1,0]
	v_pk_add_f32 v[62:63], v[62:63], v[62:63] op_sel:[0,1] op_sel_hi:[1,0]
	v_mov_b32_e32 v61, v88
	v_mov_b32_e32 v63, v87
	v_pk_add_f32 v[60:61], v[62:63], v[60:61]
	s_nop 0
	v_pk_add_f32 v[58:59], v[60:61], v[58:59]
	s_nop 0
	v_add_f32_e32 v58, v58, v59
	ds_bpermute_b32 v59, v28, v58
	s_waitcnt lgkmcnt(0)
	v_add_f32_e32 v58, v58, v59
	ds_bpermute_b32 v59, v29, v58
	s_waitcnt lgkmcnt(0)
	v_add_f32_e32 v58, v58, v59
	ds_bpermute_b32 v59, v30, v58
	s_waitcnt lgkmcnt(0)
	v_add_f32_e32 v58, v58, v59
	ds_bpermute_b32 v59, v31, v58
	s_waitcnt lgkmcnt(0)
	v_add_f32_e32 v58, v58, v59
	ds_bpermute_b32 v59, v32, v58
	s_waitcnt lgkmcnt(0)
	v_add_f32_e32 v58, v58, v59
	ds_bpermute_b32 v59, v33, v58
	s_waitcnt lgkmcnt(0)
	v_add_f32_e32 v58, v58, v59
	v_fmamk_f32 v58, v58, 0x3a000000, v34
	v_mul_f32_e32 v59, 0x4f800000, v58
	v_cmp_gt_f32_e32 vcc, s10, v58
	s_nop 1
	v_cndmask_b32_e32 v58, v58, v59, vcc
	v_sqrt_f32_e32 v59, v58
	s_nop 0
	v_add_u32_e32 v60, -1, v59
	v_add_u32_e32 v61, 1, v59
	v_fma_f32 v62, -v60, v59, v58
	v_fma_f32 v63, -v61, v59, v58
	v_cmp_ge_f32_e64 s[0:1], 0, v62
	s_nop 1
	v_cndmask_b32_e64 v59, v59, v60, s[0:1]
	v_cmp_lt_f32_e64 s[0:1], 0, v63
	s_nop 1
	v_cndmask_b32_e64 v59, v59, v61, s[0:1]
	v_mul_f32_e32 v60, 0x37800000, v59
	v_cndmask_b32_e32 v59, v59, v60, vcc
	v_cmp_class_f32_e32 vcc, v58, v35
	s_nop 1
	v_cndmask_b32_e32 v58, v59, v58, vcc
	v_div_scale_f32 v59, s[0:1], v58, v58, 1.0
	v_rcp_f32_e32 v61, v59
	v_div_scale_f32 v60, vcc, 1.0, v58, 1.0
	v_fma_f32 v62, -v59, v61, 1.0
	v_fmac_f32_e32 v61, v62, v61
	v_mul_f32_e32 v62, v60, v61
	v_fma_f32 v63, -v59, v62, v60
	v_fmac_f32_e32 v62, v63, v61
	v_fma_f32 v59, -v59, v62, v60
	v_div_fmas_f32 v59, v59, v61, v62
	v_div_fixup_f32 v58, v59, v58, 1.0
	v_pk_mul_f32 v[36:37], v[36:37], v[58:59] op_sel_hi:[1,0]
	v_pk_mul_f32 v[38:39], v[38:39], v[58:59] op_sel_hi:[1,0]
	v_pk_mul_f32 v[40:41], v[40:41], v[58:59] op_sel_hi:[1,0]
	v_pk_mul_f32 v[42:43], v[42:43], v[58:59] op_sel_hi:[1,0]
	v_pk_mul_f32 v[44:45], v[44:45], v[58:59] op_sel_hi:[1,0]
	v_pk_mul_f32 v[46:47], v[46:47], v[58:59] op_sel_hi:[1,0]
	v_pk_mul_f32 v[48:49], v[48:49], v[58:59] op_sel_hi:[1,0]
	v_pk_mul_f32 v[50:51], v[50:51], v[58:59] op_sel_hi:[1,0]
	v_pk_mul_f32 v[4:5], v[4:5], v[58:59] op_sel_hi:[1,0]
	v_pk_mul_f32 v[6:7], v[6:7], v[58:59] op_sel_hi:[1,0]
	v_pk_mul_f32 v[12:13], v[12:13], v[58:59] op_sel_hi:[1,0]
	v_pk_mul_f32 v[14:15], v[14:15], v[58:59] op_sel_hi:[1,0]
	v_pk_mul_f32 v[8:9], v[8:9], v[58:59] op_sel_hi:[1,0]
	v_pk_mul_f32 v[10:11], v[10:11], v[58:59] op_sel_hi:[1,0]
	v_pk_mul_f32 v[0:1], v[0:1], v[58:59] op_sel_hi:[1,0]
	v_pk_mul_f32 v[2:3], v[2:3], v[58:59] op_sel_hi:[1,0]
	v_add_co_u32_e32 v62, vcc, s11, v56
	s_nop 1
	v_addc_co_u32_e32 v63, vcc, 0, v57, vcc
	v_pk_mul_f32 v[36:37], v[100:101], v[36:37]
	v_pk_mul_f32 v[38:39], v[102:103], v[38:39]
	global_store_dwordx4 v[56:57], v[36:39], off nt
	v_pk_mul_f32 v[40:41], v[104:105], v[40:41]
	v_pk_mul_f32 v[42:43], v[106:107], v[42:43]
	global_store_dwordx4 v[56:57], v[40:43], off offset:1024 nt
	v_pk_mul_f32 v[44:45], v[108:109], v[44:45]
	v_pk_mul_f32 v[46:47], v[110:111], v[46:47]
	global_store_dwordx4 v[56:57], v[44:47], off offset:2048 nt
	v_pk_mul_f32 v[48:49], v[112:113], v[48:49]
	v_pk_mul_f32 v[50:51], v[114:115], v[50:51]
	global_store_dwordx4 v[56:57], v[48:51], off offset:3072 nt
	v_pk_mul_f32 v[4:5], v[116:117], v[4:5]
	v_pk_mul_f32 v[6:7], v[118:119], v[6:7]
	global_store_dwordx4 v[62:63], v[4:7], off nt
	v_pk_mul_f32 v[12:13], v[120:121], v[12:13]
	v_pk_mul_f32 v[14:15], v[122:123], v[14:15]
	global_store_dwordx4 v[62:63], v[12:15], off offset:1024 nt
	v_pk_mul_f32 v[8:9], v[124:125], v[8:9]
	v_pk_mul_f32 v[10:11], v[126:127], v[10:11]
	global_store_dwordx4 v[62:63], v[8:11], off offset:2048 nt
	v_pk_mul_f32 v[0:1], v[128:129], v[0:1]
	v_pk_mul_f32 v[2:3], v[130:131], v[2:3]
	global_store_dwordx4 v[62:63], v[0:3], off offset:3072 nt
	s_cbranch_scc1 .LBB0_1168
